# hand-written gemm1 epilogue (prefetched rope table, dwordx4 stores via permlane16_swap) + widened ffn_in stores
# speedup vs baseline: 1.0380x; 1.0380x over previous
.LBB0_612:
	s_or_b64 exec, exec, s[0:1]
	v_readlane_b32 s0, v243, 45
	v_readlane_b32 s1, v243, 46
	s_andn2_b64 vcc, exec, s[0:1]
	v_readlane_b32 s0, v240, 27
	v_readlane_b32 s1, v240, 28
	s_mov_b32 s1, s85
	v_writelane_b32 v240, s0, 27
	s_barrier
	s_nop 0
	v_writelane_b32 v240, s1, 28
	s_cbranch_vccnz .LBB0_789
	v_mov_b32_e32 v0, v166
	s_barrier
	v_readlane_b32 s24, v242, 26
	v_lshlrev_b32_e32 v2, 4, v0
	v_and_b32_e32 v3, 32, v0
	v_ashrrev_i32_e32 v1, 6, v0
	v_bitop3_b32 v2, v2, v3, 48 bitop3:0x6c
	v_lshlrev_b32_e32 v0, 8, v0
	v_lshrrev_b32_e32 v2, 1, v2
	v_and_b32_e32 v0, 0x3c00, v0
	v_lshlrev_b32_e32 v3, 14, v1
	v_or3_b32 v64, v3, v0, v2
	v_add_u32_e32 v0, 0x20000, v64
	v_lshlrev_b32_e32 v10, 10, v1
	v_mov_b32_e32 v1, v65
	v_lshlrev_b64 v[2:3], 1, v[64:65]
	v_readlane_b32 s25, v242, 27
	v_readfirstlane_b32 s0, v10
	v_lshlrev_b64 v[0:1], 1, v[0:1]
	v_add_u32_e32 v8, 0x2000, v10
	v_lshl_add_u64 v[4:5], s[24:25], 0, v[2:3]
	s_mov_b32 m0, s0
	v_lshl_add_u64 v[6:7], s[24:25], 0, v[0:1]
	v_readfirstlane_b32 s0, v8
	v_readlane_b32 s24, v241, 62
	v_add_u32_e32 v8, 0x4000, v10
	global_load_lds_dwordx4 v[4:5], off
	s_mov_b32 m0, s0
	v_readlane_b32 s25, v241, 63
	v_readfirstlane_b32 s0, v8
	v_add_u32_e32 v8, 0x6000, v10
	global_load_lds_dwordx4 v[6:7], off
	v_lshl_add_u64 v[2:3], s[24:25], 0, v[2:3]
	s_mov_b32 m0, s0
	v_readfirstlane_b32 s0, v8
	v_add_u32_e32 v11, 0x8000, v10
	global_load_lds_dwordx4 v[2:3], off
	v_lshl_add_u64 v[0:1], s[24:25], 0, v[0:1]
	s_mov_b32 m0, s0
	v_readfirstlane_b32 s0, v11
	v_add_u32_e32 v11, 0xa000, v10
	global_load_lds_dwordx4 v[0:1], off
	v_lshl_add_u64 v[8:9], v[4:5], 0, 64
	s_mov_b32 m0, s0
	v_readfirstlane_b32 s0, v11
	v_add_u32_e32 v11, 0xc000, v10
	global_load_lds_dwordx4 v[8:9], off
	v_lshl_add_u64 v[8:9], v[6:7], 0, 64
	s_mov_b32 m0, s0
	v_readfirstlane_b32 s0, v11
	v_add_u32_e32 v11, 0xe000, v10
	global_load_lds_dwordx4 v[8:9], off
	v_lshl_add_u64 v[8:9], v[2:3], 0, 64
	s_mov_b32 m0, s0
	v_readfirstlane_b32 s0, v11
	v_add_u32_e32 v11, 0x10000, v10
	global_load_lds_dwordx4 v[8:9], off
	v_lshl_add_u64 v[8:9], v[0:1], 0, 64
	s_mov_b32 m0, s0
	v_readfirstlane_b32 s0, v11
	v_add_u32_e32 v11, 0x12000, v10
	global_load_lds_dwordx4 v[8:9], off
	v_lshl_add_u64 v[8:9], v[4:5], 0, s[34:35]
	s_mov_b32 m0, s0
	v_readfirstlane_b32 s0, v11
	v_add_u32_e32 v11, 0x14000, v10
	global_load_lds_dwordx4 v[8:9], off
	v_lshl_add_u64 v[8:9], v[6:7], 0, s[34:35]
	s_mov_b32 m0, s0
	v_readfirstlane_b32 s0, v11
	v_add_u32_e32 v11, 0x16000, v10
	global_load_lds_dwordx4 v[8:9], off
	v_lshl_add_u64 v[8:9], v[2:3], 0, s[34:35]
	s_mov_b32 m0, s0
	v_readfirstlane_b32 s0, v11
	global_load_lds_dwordx4 v[8:9], off
	v_lshl_add_u64 v[8:9], v[0:1], 0, s[34:35]
	s_mov_b32 m0, s0
	v_lshl_add_u64 v[4:5], v[4:5], 0, s[82:83]
	global_load_lds_dwordx4 v[8:9], off
	v_add_u32_e32 v8, 0x18000, v10
	v_lshl_add_u64 v[2:3], v[2:3], 0, s[82:83]
	v_readfirstlane_b32 s0, v8
	s_mov_b32 m0, s0
	v_lshl_add_u64 v[0:1], v[0:1], 0, s[82:83]
	global_load_lds_dwordx4 v[4:5], off
	v_lshl_add_u64 v[4:5], v[6:7], 0, s[82:83]
	v_add_u32_e32 v6, 0x1a000, v10
	v_readlane_b32 s24, v244, 0
	v_readfirstlane_b32 s0, v6
	s_mov_b32 m0, s0
	v_readlane_b32 s25, v244, 1
	global_load_lds_dwordx4 v[4:5], off
	v_add_u32_e32 v4, 0x1c000, v10
	s_mov_b32 s78, 1
	v_readfirstlane_b32 s0, v4
	s_mov_b32 m0, s0
	s_mov_b32 s79, 0
	global_load_lds_dwordx4 v[2:3], off
	v_add_u32_e32 v2, 0x1e000, v10
	v_readlane_b32 s80, v242, 28
	v_readfirstlane_b32 s0, v2
	s_mov_b32 m0, s0
	v_readlane_b32 s0, v240, 27
	global_load_lds_dwordx4 v[0:1], off
	v_readlane_b32 s1, v240, 28
	s_lshl_b64 s[0:1], s[0:1], 20
	s_add_u32 s44, s24, s0
	s_addc_u32 s45, s25, s1
	v_readlane_b32 s28, v242, 24
	v_readlane_b32 s29, v242, 25
	s_branch .LBB0_615
.LBB0_615:
	s_lshl_b32 s24, s80, 8
	s_add_i32 s0, s24, 0x400
	v_mov_b32_e32 v0, v166
	s_cmp_lt_i32 s80, 19
	s_cselect_b32 s0, s24, s0
	v_lshlrev_b32_e32 v2, 4, v0
	v_and_b32_e32 v3, 32, v0
	v_ashrrev_i32_e32 v1, 6, v0
	v_bitop3_b32 v2, v2, v3, 48 bitop3:0x6c
	v_mov_b32_e32 v3, v166
	v_lshlrev_b32_e32 v0, 8, v0
	s_ashr_i32 s31, s28, 31
	s_mov_b32 s30, s28
	s_ashr_i32 s1, s0, 31
	v_lshrrev_b32_e32 v2, 1, v2
	v_lshlrev_b32_e32 v200, 10, v1
	v_and_b32_e32 v4, 15, v3
	v_lshlrev_b32_e32 v6, 2, v3
	v_lshlrev_b32_e32 v1, 14, v1
	v_and_b32_e32 v0, 0x3c00, v0
	s_lshl_b64 s[26:27], s[30:31], 19
	s_lshl_b64 s[0:1], s[0:1], 11
	v_and_b32_e32 v5, 48, v3
	v_lshlrev_b32_e32 v4, 6, v4
	v_and_b32_e32 v6, 32, v6
	v_or3_b32 v0, v2, v1, v0
	v_readlane_b32 s25, v240, 16
	v_bitop3_b32 v197, v4, v6, v5 bitop3:0x36
	v_lshlrev_b32_e32 v4, 5, v3
	v_lshlrev_b32_e32 v3, 6, v3
	v_add_u32_e32 v64, 0x20000, v0
	s_add_u32 s0, s25, s0
	v_readlane_b32 s25, v240, 17
	v_mov_b32_e32 v1, v65
	v_and_b32_e32 v199, 0x3000, v3
	v_lshlrev_b64 v[2:3], 1, v[64:65]
	s_addc_u32 s1, s25, s1
	v_lshlrev_b64 v[0:1], 1, v[0:1]
	v_lshl_add_u64 v[158:159], s[0:1], 0, v[2:3]
	v_lshl_add_u64 v[160:161], s[0:1], 0, v[0:1]
	v_readlane_b32 s0, v242, 57
	s_add_u32 s0, s0, s26
	v_readlane_b32 s1, v242, 58
	s_addc_u32 s1, s1, s27
	v_and_b32_e32 v198, 0xffffe000, v4
	v_lshl_add_u64 v[164:165], s[0:1], 0, v[0:1]
	v_mov_b32_e32 v0, 0
	v_lshl_add_u64 v[162:163], s[0:1], 0, v[2:3]
	s_mov_b64 s[0:1], 0
	s_mov_b32 s25, 0
	v_mov_b32_e32 v1, v0
	v_mov_b32_e32 v2, v0
	v_mov_b32_e32 v3, v0
	v_mov_b32_e32 v28, v0
	v_mov_b32_e32 v29, v0
	v_mov_b32_e32 v30, v0
	v_mov_b32_e32 v31, v0
	v_mov_b32_e32 v66, v0
	v_mov_b32_e32 v67, v0
	v_mov_b32_e32 v68, v0
	v_mov_b32_e32 v69, v0
	v_mov_b32_e32 v98, v0
	v_mov_b32_e32 v99, v0
	v_mov_b32_e32 v100, v0
	v_mov_b32_e32 v101, v0
	v_mov_b32_e32 v4, v0
	v_mov_b32_e32 v5, v0
	v_mov_b32_e32 v6, v0
	v_mov_b32_e32 v7, v0
	v_mov_b32_e32 v36, v0
	v_mov_b32_e32 v37, v0
	v_mov_b32_e32 v38, v0
	v_mov_b32_e32 v39, v0
	v_mov_b32_e32 v70, v0
	v_mov_b32_e32 v71, v0
	v_mov_b32_e32 v72, v0
	v_mov_b32_e32 v73, v0
	v_mov_b32_e32 v102, v0
	v_mov_b32_e32 v103, v0
	v_mov_b32_e32 v104, v0
	v_mov_b32_e32 v105, v0
	v_mov_b32_e32 v8, v0
	v_mov_b32_e32 v9, v0
	v_mov_b32_e32 v10, v0
	v_mov_b32_e32 v11, v0
	v_mov_b32_e32 v40, v0
	v_mov_b32_e32 v41, v0
	v_mov_b32_e32 v42, v0
	v_mov_b32_e32 v43, v0
	v_mov_b32_e32 v74, v0
	v_mov_b32_e32 v75, v0
	v_mov_b32_e32 v76, v0
	v_mov_b32_e32 v77, v0
	v_mov_b32_e32 v106, v0
	v_mov_b32_e32 v107, v0
	v_mov_b32_e32 v108, v0
	v_mov_b32_e32 v109, v0
	v_mov_b32_e32 v12, v0
	v_mov_b32_e32 v13, v0
	v_mov_b32_e32 v14, v0
	v_mov_b32_e32 v15, v0
	v_mov_b32_e32 v44, v0
	v_mov_b32_e32 v45, v0
	v_mov_b32_e32 v46, v0
	v_mov_b32_e32 v47, v0
	v_mov_b32_e32 v78, v0
	v_mov_b32_e32 v79, v0
	v_mov_b32_e32 v80, v0
	v_mov_b32_e32 v81, v0
	v_mov_b32_e32 v110, v0
	v_mov_b32_e32 v111, v0
	v_mov_b32_e32 v112, v0
	v_mov_b32_e32 v113, v0
	v_mov_b32_e32 v16, v0
	v_mov_b32_e32 v17, v0
	v_mov_b32_e32 v18, v0
	v_mov_b32_e32 v19, v0
	v_mov_b32_e32 v48, v0
	v_mov_b32_e32 v49, v0
	v_mov_b32_e32 v50, v0
	v_mov_b32_e32 v51, v0
	v_mov_b32_e32 v82, v0
	v_mov_b32_e32 v83, v0
	v_mov_b32_e32 v84, v0
	v_mov_b32_e32 v85, v0
	v_mov_b32_e32 v114, v0
	v_mov_b32_e32 v115, v0
	v_mov_b32_e32 v116, v0
	v_mov_b32_e32 v117, v0
	v_mov_b32_e32 v20, v0
	v_mov_b32_e32 v21, v0
	v_mov_b32_e32 v22, v0
	v_mov_b32_e32 v23, v0
	v_mov_b32_e32 v52, v0
	v_mov_b32_e32 v53, v0
	v_mov_b32_e32 v54, v0
	v_mov_b32_e32 v55, v0
	v_mov_b32_e32 v86, v0
	v_mov_b32_e32 v87, v0
	v_mov_b32_e32 v88, v0
	v_mov_b32_e32 v89, v0
	v_mov_b32_e32 v118, v0
	v_mov_b32_e32 v119, v0
	v_mov_b32_e32 v120, v0
	v_mov_b32_e32 v121, v0
	v_mov_b32_e32 v24, v0
	v_mov_b32_e32 v25, v0
	v_mov_b32_e32 v26, v0
	v_mov_b32_e32 v27, v0
	v_mov_b32_e32 v56, v0
	v_mov_b32_e32 v57, v0
	v_mov_b32_e32 v58, v0
	v_mov_b32_e32 v59, v0
	v_mov_b32_e32 v90, v0
	v_mov_b32_e32 v91, v0
	v_mov_b32_e32 v92, v0
	v_mov_b32_e32 v93, v0
	v_mov_b32_e32 v122, v0
	v_mov_b32_e32 v123, v0
	v_mov_b32_e32 v124, v0
	v_mov_b32_e32 v125, v0
	v_mov_b32_e32 v32, v0
	v_mov_b32_e32 v33, v0
	v_mov_b32_e32 v34, v0
	v_mov_b32_e32 v35, v0
	v_mov_b32_e32 v60, v0
	v_mov_b32_e32 v61, v0
	v_mov_b32_e32 v62, v0
	v_mov_b32_e32 v63, v0
	v_mov_b32_e32 v94, v0
	v_mov_b32_e32 v95, v0
	v_mov_b32_e32 v96, v0
	v_mov_b32_e32 v97, v0
	v_mov_b32_e32 v126, v0
	v_mov_b32_e32 v127, v0
	v_mov_b32_e32 v128, v0
	v_mov_b32_e32 v129, v0
	s_branch .LBB0_617

.LBB0_644:
	v_readfirstlane_b32 s25, v166
	s_mul_hi_i32 s1, s30, 0x460000
	s_mul_i32 s0, s30, 0x460000
	s_and_b32 s38, s25, 0xc0
	s_or_b32 s29, s38, s24
	s_add_u32 s0, s18, s0
	s_addc_u32 s1, s19, s1
	s_ashr_i32 s31, s30, 31
	s_lshl_b64 s[36:37], s[30:31], 14
	s_add_u32 s64, s44, s36
	s_addc_u32 s65, s45, s37
	v_and_b32_e32 v248, 15, v166
	v_lshrrev_b32_e32 v249, 1, v166
	v_and_b32_e32 v249, 0x80, v249
	v_or_b32_e32 v248, v248, v249
	v_and_b32_e32 v249, 16, v166
	v_lshrrev_b32_e32 v250, 2, v166
	v_and_b32_e32 v250, 8, v250
	v_or_b32_e32 v249, v249, v250
	v_mul_u32_u24_e32 v250, 0x2300, v248
	v_add3_u32 v250, v250, v249, s29
	v_mov_b32_e32 v251, 0
	v_lshl_add_u64 v[246:247], v[250:251], 1, s[0:1]
	s_mov_b32 s26, 1.0
	s_cmpk_lt_u32 s29, 0x900
	s_cbranch_scc0 .Le1_b
	s_cmpk_ge_u32 s29, 0x600
	s_cselect_b32 s27, 0x600, 0
	s_sub_u32 s36, s29, s27
	s_cmpk_ge_u32 s36, 0x300
	s_cselect_b32 s27, 0x300, 0
	s_sub_u32 s36, s36, s27
	s_cmpk_lt_u32 s36, 0x100
	s_cselect_b32 s26, 0x3e000000, s26
	s_cmpk_lt_u32 s36, 0x200
	s_cbranch_scc1 .Le1_rot
	s_branch .Le1_plain
.Le1_b:
	s_cmpk_lt_u32 s29, 0xf00
	s_cbranch_scc0 .Le1_c
	s_sub_u32 s36, s29, 0x900
	s_cmpk_lt_u32 s36, 0x200
	s_cselect_b32 s26, 0x3e000000, s26
	s_cmpk_lt_u32 s36, 0x400
	s_cbranch_scc1 .Le1_rot
	s_branch .Le1_plain
.Le1_c:
	s_cmpk_lt_u32 s29, 0x1300
	s_cbranch_scc1 .Le1_plain
.Le1_gate:
	v_mul_f32_e32 v126, 0xbfb8aa3b, v126
	v_mul_f32_e32 v127, 0xbfb8aa3b, v127
	v_mul_f32_e32 v128, 0xbfb8aa3b, v128
	v_mul_f32_e32 v129, 0xbfb8aa3b, v129
	v_mul_f32_e32 v94, 0xbfb8aa3b, v94
	v_mul_f32_e32 v95, 0xbfb8aa3b, v95
	v_mul_f32_e32 v96, 0xbfb8aa3b, v96
	v_mul_f32_e32 v97, 0xbfb8aa3b, v97
	v_mul_f32_e32 v60, 0xbfb8aa3b, v60
	v_mul_f32_e32 v61, 0xbfb8aa3b, v61
	v_mul_f32_e32 v62, 0xbfb8aa3b, v62
	v_mul_f32_e32 v63, 0xbfb8aa3b, v63
	v_mul_f32_e32 v32, 0xbfb8aa3b, v32
	v_mul_f32_e32 v33, 0xbfb8aa3b, v33
	v_mul_f32_e32 v34, 0xbfb8aa3b, v34
	v_mul_f32_e32 v35, 0xbfb8aa3b, v35
	v_exp_f32_e32 v126, v126
	v_exp_f32_e32 v127, v127
	v_exp_f32_e32 v128, v128
	v_exp_f32_e32 v129, v129
	v_exp_f32_e32 v94, v94
	v_exp_f32_e32 v95, v95
	v_exp_f32_e32 v96, v96
	v_exp_f32_e32 v97, v97
	v_exp_f32_e32 v60, v60
	v_exp_f32_e32 v61, v61
	v_exp_f32_e32 v62, v62
	v_exp_f32_e32 v63, v63
	v_exp_f32_e32 v32, v32
	v_exp_f32_e32 v33, v33
	v_exp_f32_e32 v34, v34
	v_exp_f32_e32 v35, v35
	v_add_f32_e32 v126, 1.0, v126
	v_add_f32_e32 v127, 1.0, v127
	v_add_f32_e32 v128, 1.0, v128
	v_add_f32_e32 v129, 1.0, v129
	v_add_f32_e32 v94, 1.0, v94
	v_add_f32_e32 v95, 1.0, v95
	v_add_f32_e32 v96, 1.0, v96
	v_add_f32_e32 v97, 1.0, v97
	v_add_f32_e32 v60, 1.0, v60
	v_add_f32_e32 v61, 1.0, v61
	v_add_f32_e32 v62, 1.0, v62
	v_add_f32_e32 v63, 1.0, v63
	v_add_f32_e32 v32, 1.0, v32
	v_add_f32_e32 v33, 1.0, v33
	v_add_f32_e32 v34, 1.0, v34
	v_add_f32_e32 v35, 1.0, v35
	v_rcp_f32_e32 v126, v126
	v_rcp_f32_e32 v127, v127
	v_rcp_f32_e32 v128, v128
	v_rcp_f32_e32 v129, v129
	v_rcp_f32_e32 v94, v94
	v_rcp_f32_e32 v95, v95
	v_rcp_f32_e32 v96, v96
	v_rcp_f32_e32 v97, v97
	v_rcp_f32_e32 v60, v60
	v_rcp_f32_e32 v61, v61
	v_rcp_f32_e32 v62, v62
	v_rcp_f32_e32 v63, v63
	v_rcp_f32_e32 v32, v32
	v_rcp_f32_e32 v33, v33
	v_rcp_f32_e32 v34, v34
	v_rcp_f32_e32 v35, v35
	v_cvt_pk_bf16_f32 v126, v126, v127
	v_cvt_pk_bf16_f32 v127, v128, v129
	v_cvt_pk_bf16_f32 v128, v94, v95
	v_cvt_pk_bf16_f32 v129, v96, v97
	v_cvt_pk_bf16_f32 v60, v60, v61
	v_cvt_pk_bf16_f32 v61, v62, v63
	v_cvt_pk_bf16_f32 v62, v32, v33
	v_cvt_pk_bf16_f32 v63, v34, v35
	s_nop 1
	v_permlane16_swap_b32_e32 v126, v128
	v_permlane16_swap_b32_e32 v127, v129
	v_permlane16_swap_b32_e32 v60, v62
	v_permlane16_swap_b32_e32 v61, v63
	global_store_dwordx4 v[246:247], v[126:129], off
	global_store_dwordx4 v[246:247], v[60:63], off offset:64
	v_add_co_u32_e32 v246, vcc, 0x46000, v246
	s_nop 1
	v_addc_co_u32_e32 v247, vcc, 0, v247, vcc
	v_mul_f32_e32 v122, 0xbfb8aa3b, v122
	v_mul_f32_e32 v123, 0xbfb8aa3b, v123
	v_mul_f32_e32 v124, 0xbfb8aa3b, v124
	v_mul_f32_e32 v125, 0xbfb8aa3b, v125
	v_mul_f32_e32 v90, 0xbfb8aa3b, v90
	v_mul_f32_e32 v91, 0xbfb8aa3b, v91
	v_mul_f32_e32 v92, 0xbfb8aa3b, v92
	v_mul_f32_e32 v93, 0xbfb8aa3b, v93
	v_mul_f32_e32 v56, 0xbfb8aa3b, v56
	v_mul_f32_e32 v57, 0xbfb8aa3b, v57
	v_mul_f32_e32 v58, 0xbfb8aa3b, v58
	v_mul_f32_e32 v59, 0xbfb8aa3b, v59
	v_mul_f32_e32 v24, 0xbfb8aa3b, v24
	v_mul_f32_e32 v25, 0xbfb8aa3b, v25
	v_mul_f32_e32 v26, 0xbfb8aa3b, v26
	v_mul_f32_e32 v27, 0xbfb8aa3b, v27
	v_exp_f32_e32 v122, v122
	v_exp_f32_e32 v123, v123
	v_exp_f32_e32 v124, v124
	v_exp_f32_e32 v125, v125
	v_exp_f32_e32 v90, v90
	v_exp_f32_e32 v91, v91
	v_exp_f32_e32 v92, v92
	v_exp_f32_e32 v93, v93
	v_exp_f32_e32 v56, v56
	v_exp_f32_e32 v57, v57
	v_exp_f32_e32 v58, v58
	v_exp_f32_e32 v59, v59
	v_exp_f32_e32 v24, v24
	v_exp_f32_e32 v25, v25
	v_exp_f32_e32 v26, v26
	v_exp_f32_e32 v27, v27
	v_add_f32_e32 v122, 1.0, v122
	v_add_f32_e32 v123, 1.0, v123
	v_add_f32_e32 v124, 1.0, v124
	v_add_f32_e32 v125, 1.0, v125
	v_add_f32_e32 v90, 1.0, v90
	v_add_f32_e32 v91, 1.0, v91
	v_add_f32_e32 v92, 1.0, v92
	v_add_f32_e32 v93, 1.0, v93
	v_add_f32_e32 v56, 1.0, v56
	v_add_f32_e32 v57, 1.0, v57
	v_add_f32_e32 v58, 1.0, v58
	v_add_f32_e32 v59, 1.0, v59
	v_add_f32_e32 v24, 1.0, v24
	v_add_f32_e32 v25, 1.0, v25
	v_add_f32_e32 v26, 1.0, v26
	v_add_f32_e32 v27, 1.0, v27
	v_rcp_f32_e32 v122, v122
	v_rcp_f32_e32 v123, v123
	v_rcp_f32_e32 v124, v124
	v_rcp_f32_e32 v125, v125
	v_rcp_f32_e32 v90, v90
	v_rcp_f32_e32 v91, v91
	v_rcp_f32_e32 v92, v92
	v_rcp_f32_e32 v93, v93
	v_rcp_f32_e32 v56, v56
	v_rcp_f32_e32 v57, v57
	v_rcp_f32_e32 v58, v58
	v_rcp_f32_e32 v59, v59
	v_rcp_f32_e32 v24, v24
	v_rcp_f32_e32 v25, v25
	v_rcp_f32_e32 v26, v26
	v_rcp_f32_e32 v27, v27
	v_cvt_pk_bf16_f32 v122, v122, v123
	v_cvt_pk_bf16_f32 v123, v124, v125
	v_cvt_pk_bf16_f32 v124, v90, v91
	v_cvt_pk_bf16_f32 v125, v92, v93
	v_cvt_pk_bf16_f32 v56, v56, v57
	v_cvt_pk_bf16_f32 v57, v58, v59
	v_cvt_pk_bf16_f32 v58, v24, v25
	v_cvt_pk_bf16_f32 v59, v26, v27
	s_nop 1
	v_permlane16_swap_b32_e32 v122, v124
	v_permlane16_swap_b32_e32 v123, v125
	v_permlane16_swap_b32_e32 v56, v58
	v_permlane16_swap_b32_e32 v57, v59
	global_store_dwordx4 v[246:247], v[122:125], off
	global_store_dwordx4 v[246:247], v[56:59], off offset:64
	v_add_co_u32_e32 v246, vcc, 0x46000, v246
	s_nop 1
	v_addc_co_u32_e32 v247, vcc, 0, v247, vcc
	v_mul_f32_e32 v118, 0xbfb8aa3b, v118
	v_mul_f32_e32 v119, 0xbfb8aa3b, v119
	v_mul_f32_e32 v120, 0xbfb8aa3b, v120
	v_mul_f32_e32 v121, 0xbfb8aa3b, v121
	v_mul_f32_e32 v86, 0xbfb8aa3b, v86
	v_mul_f32_e32 v87, 0xbfb8aa3b, v87
	v_mul_f32_e32 v88, 0xbfb8aa3b, v88
	v_mul_f32_e32 v89, 0xbfb8aa3b, v89
	v_mul_f32_e32 v52, 0xbfb8aa3b, v52
	v_mul_f32_e32 v53, 0xbfb8aa3b, v53
	v_mul_f32_e32 v54, 0xbfb8aa3b, v54
	v_mul_f32_e32 v55, 0xbfb8aa3b, v55
	v_mul_f32_e32 v20, 0xbfb8aa3b, v20
	v_mul_f32_e32 v21, 0xbfb8aa3b, v21
	v_mul_f32_e32 v22, 0xbfb8aa3b, v22
	v_mul_f32_e32 v23, 0xbfb8aa3b, v23
	v_exp_f32_e32 v118, v118
	v_exp_f32_e32 v119, v119
	v_exp_f32_e32 v120, v120
	v_exp_f32_e32 v121, v121
	v_exp_f32_e32 v86, v86
	v_exp_f32_e32 v87, v87
	v_exp_f32_e32 v88, v88
	v_exp_f32_e32 v89, v89
	v_exp_f32_e32 v52, v52
	v_exp_f32_e32 v53, v53
	v_exp_f32_e32 v54, v54
	v_exp_f32_e32 v55, v55
	v_exp_f32_e32 v20, v20
	v_exp_f32_e32 v21, v21
	v_exp_f32_e32 v22, v22
	v_exp_f32_e32 v23, v23
	v_add_f32_e32 v118, 1.0, v118
	v_add_f32_e32 v119, 1.0, v119
	v_add_f32_e32 v120, 1.0, v120
	v_add_f32_e32 v121, 1.0, v121
	v_add_f32_e32 v86, 1.0, v86
	v_add_f32_e32 v87, 1.0, v87
	v_add_f32_e32 v88, 1.0, v88
	v_add_f32_e32 v89, 1.0, v89
	v_add_f32_e32 v52, 1.0, v52
	v_add_f32_e32 v53, 1.0, v53
	v_add_f32_e32 v54, 1.0, v54
	v_add_f32_e32 v55, 1.0, v55
	v_add_f32_e32 v20, 1.0, v20
	v_add_f32_e32 v21, 1.0, v21
	v_add_f32_e32 v22, 1.0, v22
	v_add_f32_e32 v23, 1.0, v23
	v_rcp_f32_e32 v118, v118
	v_rcp_f32_e32 v119, v119
	v_rcp_f32_e32 v120, v120
	v_rcp_f32_e32 v121, v121
	v_rcp_f32_e32 v86, v86
	v_rcp_f32_e32 v87, v87
	v_rcp_f32_e32 v88, v88
	v_rcp_f32_e32 v89, v89
	v_rcp_f32_e32 v52, v52
	v_rcp_f32_e32 v53, v53
	v_rcp_f32_e32 v54, v54
	v_rcp_f32_e32 v55, v55
	v_rcp_f32_e32 v20, v20
	v_rcp_f32_e32 v21, v21
	v_rcp_f32_e32 v22, v22
	v_rcp_f32_e32 v23, v23
	v_cvt_pk_bf16_f32 v118, v118, v119
	v_cvt_pk_bf16_f32 v119, v120, v121
	v_cvt_pk_bf16_f32 v120, v86, v87
	v_cvt_pk_bf16_f32 v121, v88, v89
	v_cvt_pk_bf16_f32 v52, v52, v53
	v_cvt_pk_bf16_f32 v53, v54, v55
	v_cvt_pk_bf16_f32 v54, v20, v21
	v_cvt_pk_bf16_f32 v55, v22, v23
	s_nop 1
	v_permlane16_swap_b32_e32 v118, v120
	v_permlane16_swap_b32_e32 v119, v121
	v_permlane16_swap_b32_e32 v52, v54
	v_permlane16_swap_b32_e32 v53, v55
	global_store_dwordx4 v[246:247], v[118:121], off
	global_store_dwordx4 v[246:247], v[52:55], off offset:64
	v_add_co_u32_e32 v246, vcc, 0x46000, v246
	s_nop 1
	v_addc_co_u32_e32 v247, vcc, 0, v247, vcc
	v_mul_f32_e32 v114, 0xbfb8aa3b, v114
	v_mul_f32_e32 v115, 0xbfb8aa3b, v115
	v_mul_f32_e32 v116, 0xbfb8aa3b, v116
	v_mul_f32_e32 v117, 0xbfb8aa3b, v117
	v_mul_f32_e32 v82, 0xbfb8aa3b, v82
	v_mul_f32_e32 v83, 0xbfb8aa3b, v83
	v_mul_f32_e32 v84, 0xbfb8aa3b, v84
	v_mul_f32_e32 v85, 0xbfb8aa3b, v85
	v_mul_f32_e32 v48, 0xbfb8aa3b, v48
	v_mul_f32_e32 v49, 0xbfb8aa3b, v49
	v_mul_f32_e32 v50, 0xbfb8aa3b, v50
	v_mul_f32_e32 v51, 0xbfb8aa3b, v51
	v_mul_f32_e32 v16, 0xbfb8aa3b, v16
	v_mul_f32_e32 v17, 0xbfb8aa3b, v17
	v_mul_f32_e32 v18, 0xbfb8aa3b, v18
	v_mul_f32_e32 v19, 0xbfb8aa3b, v19
	v_exp_f32_e32 v114, v114
	v_exp_f32_e32 v115, v115
	v_exp_f32_e32 v116, v116
	v_exp_f32_e32 v117, v117
	v_exp_f32_e32 v82, v82
	v_exp_f32_e32 v83, v83
	v_exp_f32_e32 v84, v84
	v_exp_f32_e32 v85, v85
	v_exp_f32_e32 v48, v48
	v_exp_f32_e32 v49, v49
	v_exp_f32_e32 v50, v50
	v_exp_f32_e32 v51, v51
	v_exp_f32_e32 v16, v16
	v_exp_f32_e32 v17, v17
	v_exp_f32_e32 v18, v18
	v_exp_f32_e32 v19, v19
	v_add_f32_e32 v114, 1.0, v114
	v_add_f32_e32 v115, 1.0, v115
	v_add_f32_e32 v116, 1.0, v116
	v_add_f32_e32 v117, 1.0, v117
	v_add_f32_e32 v82, 1.0, v82
	v_add_f32_e32 v83, 1.0, v83
	v_add_f32_e32 v84, 1.0, v84
	v_add_f32_e32 v85, 1.0, v85
	v_add_f32_e32 v48, 1.0, v48
	v_add_f32_e32 v49, 1.0, v49
	v_add_f32_e32 v50, 1.0, v50
	v_add_f32_e32 v51, 1.0, v51
	v_add_f32_e32 v16, 1.0, v16
	v_add_f32_e32 v17, 1.0, v17
	v_add_f32_e32 v18, 1.0, v18
	v_add_f32_e32 v19, 1.0, v19
	v_rcp_f32_e32 v114, v114
	v_rcp_f32_e32 v115, v115
	v_rcp_f32_e32 v116, v116
	v_rcp_f32_e32 v117, v117
	v_rcp_f32_e32 v82, v82
	v_rcp_f32_e32 v83, v83
	v_rcp_f32_e32 v84, v84
	v_rcp_f32_e32 v85, v85
	v_rcp_f32_e32 v48, v48
	v_rcp_f32_e32 v49, v49
	v_rcp_f32_e32 v50, v50
	v_rcp_f32_e32 v51, v51
	v_rcp_f32_e32 v16, v16
	v_rcp_f32_e32 v17, v17
	v_rcp_f32_e32 v18, v18
	v_rcp_f32_e32 v19, v19
	v_cvt_pk_bf16_f32 v114, v114, v115
	v_cvt_pk_bf16_f32 v115, v116, v117
	v_cvt_pk_bf16_f32 v116, v82, v83
	v_cvt_pk_bf16_f32 v117, v84, v85
	v_cvt_pk_bf16_f32 v48, v48, v49
	v_cvt_pk_bf16_f32 v49, v50, v51
	v_cvt_pk_bf16_f32 v50, v16, v17
	v_cvt_pk_bf16_f32 v51, v18, v19
	s_nop 1
	v_permlane16_swap_b32_e32 v114, v116
	v_permlane16_swap_b32_e32 v115, v117
	v_permlane16_swap_b32_e32 v48, v50
	v_permlane16_swap_b32_e32 v49, v51
	global_store_dwordx4 v[246:247], v[114:117], off
	global_store_dwordx4 v[246:247], v[48:51], off offset:64
	v_add_co_u32_e32 v246, vcc, 0x46000, v246
	s_nop 1
	v_addc_co_u32_e32 v247, vcc, 0, v247, vcc
	v_mul_f32_e32 v110, 0xbfb8aa3b, v110
	v_mul_f32_e32 v111, 0xbfb8aa3b, v111
	v_mul_f32_e32 v112, 0xbfb8aa3b, v112
	v_mul_f32_e32 v113, 0xbfb8aa3b, v113
	v_mul_f32_e32 v78, 0xbfb8aa3b, v78
	v_mul_f32_e32 v79, 0xbfb8aa3b, v79
	v_mul_f32_e32 v80, 0xbfb8aa3b, v80
	v_mul_f32_e32 v81, 0xbfb8aa3b, v81
	v_mul_f32_e32 v44, 0xbfb8aa3b, v44
	v_mul_f32_e32 v45, 0xbfb8aa3b, v45
	v_mul_f32_e32 v46, 0xbfb8aa3b, v46
	v_mul_f32_e32 v47, 0xbfb8aa3b, v47
	v_mul_f32_e32 v12, 0xbfb8aa3b, v12
	v_mul_f32_e32 v13, 0xbfb8aa3b, v13
	v_mul_f32_e32 v14, 0xbfb8aa3b, v14
	v_mul_f32_e32 v15, 0xbfb8aa3b, v15
	v_exp_f32_e32 v110, v110
	v_exp_f32_e32 v111, v111
	v_exp_f32_e32 v112, v112
	v_exp_f32_e32 v113, v113
	v_exp_f32_e32 v78, v78
	v_exp_f32_e32 v79, v79
	v_exp_f32_e32 v80, v80
	v_exp_f32_e32 v81, v81
	v_exp_f32_e32 v44, v44
	v_exp_f32_e32 v45, v45
	v_exp_f32_e32 v46, v46
	v_exp_f32_e32 v47, v47
	v_exp_f32_e32 v12, v12
	v_exp_f32_e32 v13, v13
	v_exp_f32_e32 v14, v14
	v_exp_f32_e32 v15, v15
	v_add_f32_e32 v110, 1.0, v110
	v_add_f32_e32 v111, 1.0, v111
	v_add_f32_e32 v112, 1.0, v112
	v_add_f32_e32 v113, 1.0, v113
	v_add_f32_e32 v78, 1.0, v78
	v_add_f32_e32 v79, 1.0, v79
	v_add_f32_e32 v80, 1.0, v80
	v_add_f32_e32 v81, 1.0, v81
	v_add_f32_e32 v44, 1.0, v44
	v_add_f32_e32 v45, 1.0, v45
	v_add_f32_e32 v46, 1.0, v46
	v_add_f32_e32 v47, 1.0, v47
	v_add_f32_e32 v12, 1.0, v12
	v_add_f32_e32 v13, 1.0, v13
	v_add_f32_e32 v14, 1.0, v14
	v_add_f32_e32 v15, 1.0, v15
	v_rcp_f32_e32 v110, v110
	v_rcp_f32_e32 v111, v111
	v_rcp_f32_e32 v112, v112
	v_rcp_f32_e32 v113, v113
	v_rcp_f32_e32 v78, v78
	v_rcp_f32_e32 v79, v79
	v_rcp_f32_e32 v80, v80
	v_rcp_f32_e32 v81, v81
	v_rcp_f32_e32 v44, v44
	v_rcp_f32_e32 v45, v45
	v_rcp_f32_e32 v46, v46
	v_rcp_f32_e32 v47, v47
	v_rcp_f32_e32 v12, v12
	v_rcp_f32_e32 v13, v13
	v_rcp_f32_e32 v14, v14
	v_rcp_f32_e32 v15, v15
	v_cvt_pk_bf16_f32 v110, v110, v111
	v_cvt_pk_bf16_f32 v111, v112, v113
	v_cvt_pk_bf16_f32 v112, v78, v79
	v_cvt_pk_bf16_f32 v113, v80, v81
	v_cvt_pk_bf16_f32 v44, v44, v45
	v_cvt_pk_bf16_f32 v45, v46, v47
	v_cvt_pk_bf16_f32 v46, v12, v13
	v_cvt_pk_bf16_f32 v47, v14, v15
	s_nop 1
	v_permlane16_swap_b32_e32 v110, v112
	v_permlane16_swap_b32_e32 v111, v113
	v_permlane16_swap_b32_e32 v44, v46
	v_permlane16_swap_b32_e32 v45, v47
	global_store_dwordx4 v[246:247], v[110:113], off
	global_store_dwordx4 v[246:247], v[44:47], off offset:64
	v_add_co_u32_e32 v246, vcc, 0x46000, v246
	s_nop 1
	v_addc_co_u32_e32 v247, vcc, 0, v247, vcc
	v_mul_f32_e32 v106, 0xbfb8aa3b, v106
	v_mul_f32_e32 v107, 0xbfb8aa3b, v107
	v_mul_f32_e32 v108, 0xbfb8aa3b, v108
	v_mul_f32_e32 v109, 0xbfb8aa3b, v109
	v_mul_f32_e32 v74, 0xbfb8aa3b, v74
	v_mul_f32_e32 v75, 0xbfb8aa3b, v75
	v_mul_f32_e32 v76, 0xbfb8aa3b, v76
	v_mul_f32_e32 v77, 0xbfb8aa3b, v77
	v_mul_f32_e32 v40, 0xbfb8aa3b, v40
	v_mul_f32_e32 v41, 0xbfb8aa3b, v41
	v_mul_f32_e32 v42, 0xbfb8aa3b, v42
	v_mul_f32_e32 v43, 0xbfb8aa3b, v43
	v_mul_f32_e32 v8, 0xbfb8aa3b, v8
	v_mul_f32_e32 v9, 0xbfb8aa3b, v9
	v_mul_f32_e32 v10, 0xbfb8aa3b, v10
	v_mul_f32_e32 v11, 0xbfb8aa3b, v11
	v_exp_f32_e32 v106, v106
	v_exp_f32_e32 v107, v107
	v_exp_f32_e32 v108, v108
	v_exp_f32_e32 v109, v109
	v_exp_f32_e32 v74, v74
	v_exp_f32_e32 v75, v75
	v_exp_f32_e32 v76, v76
	v_exp_f32_e32 v77, v77
	v_exp_f32_e32 v40, v40
	v_exp_f32_e32 v41, v41
	v_exp_f32_e32 v42, v42
	v_exp_f32_e32 v43, v43
	v_exp_f32_e32 v8, v8
	v_exp_f32_e32 v9, v9
	v_exp_f32_e32 v10, v10
	v_exp_f32_e32 v11, v11
	v_add_f32_e32 v106, 1.0, v106
	v_add_f32_e32 v107, 1.0, v107
	v_add_f32_e32 v108, 1.0, v108
	v_add_f32_e32 v109, 1.0, v109
	v_add_f32_e32 v74, 1.0, v74
	v_add_f32_e32 v75, 1.0, v75
	v_add_f32_e32 v76, 1.0, v76
	v_add_f32_e32 v77, 1.0, v77
	v_add_f32_e32 v40, 1.0, v40
	v_add_f32_e32 v41, 1.0, v41
	v_add_f32_e32 v42, 1.0, v42
	v_add_f32_e32 v43, 1.0, v43
	v_add_f32_e32 v8, 1.0, v8
	v_add_f32_e32 v9, 1.0, v9
	v_add_f32_e32 v10, 1.0, v10
	v_add_f32_e32 v11, 1.0, v11
	v_rcp_f32_e32 v106, v106
	v_rcp_f32_e32 v107, v107
	v_rcp_f32_e32 v108, v108
	v_rcp_f32_e32 v109, v109
	v_rcp_f32_e32 v74, v74
	v_rcp_f32_e32 v75, v75
	v_rcp_f32_e32 v76, v76
	v_rcp_f32_e32 v77, v77
	v_rcp_f32_e32 v40, v40
	v_rcp_f32_e32 v41, v41
	v_rcp_f32_e32 v42, v42
	v_rcp_f32_e32 v43, v43
	v_rcp_f32_e32 v8, v8
	v_rcp_f32_e32 v9, v9
	v_rcp_f32_e32 v10, v10
	v_rcp_f32_e32 v11, v11
	v_cvt_pk_bf16_f32 v106, v106, v107
	v_cvt_pk_bf16_f32 v107, v108, v109
	v_cvt_pk_bf16_f32 v108, v74, v75
	v_cvt_pk_bf16_f32 v109, v76, v77
	v_cvt_pk_bf16_f32 v40, v40, v41
	v_cvt_pk_bf16_f32 v41, v42, v43
	v_cvt_pk_bf16_f32 v42, v8, v9
	v_cvt_pk_bf16_f32 v43, v10, v11
	s_nop 1
	v_permlane16_swap_b32_e32 v106, v108
	v_permlane16_swap_b32_e32 v107, v109
	v_permlane16_swap_b32_e32 v40, v42
	v_permlane16_swap_b32_e32 v41, v43
	global_store_dwordx4 v[246:247], v[106:109], off
	global_store_dwordx4 v[246:247], v[40:43], off offset:64
	v_add_co_u32_e32 v246, vcc, 0x46000, v246
	s_nop 1
	v_addc_co_u32_e32 v247, vcc, 0, v247, vcc
	v_mul_f32_e32 v102, 0xbfb8aa3b, v102
	v_mul_f32_e32 v103, 0xbfb8aa3b, v103
	v_mul_f32_e32 v104, 0xbfb8aa3b, v104
	v_mul_f32_e32 v105, 0xbfb8aa3b, v105
	v_mul_f32_e32 v70, 0xbfb8aa3b, v70
	v_mul_f32_e32 v71, 0xbfb8aa3b, v71
	v_mul_f32_e32 v72, 0xbfb8aa3b, v72
	v_mul_f32_e32 v73, 0xbfb8aa3b, v73
	v_mul_f32_e32 v36, 0xbfb8aa3b, v36
	v_mul_f32_e32 v37, 0xbfb8aa3b, v37
	v_mul_f32_e32 v38, 0xbfb8aa3b, v38
	v_mul_f32_e32 v39, 0xbfb8aa3b, v39
	v_mul_f32_e32 v4, 0xbfb8aa3b, v4
	v_mul_f32_e32 v5, 0xbfb8aa3b, v5
	v_mul_f32_e32 v6, 0xbfb8aa3b, v6
	v_mul_f32_e32 v7, 0xbfb8aa3b, v7
	v_exp_f32_e32 v102, v102
	v_exp_f32_e32 v103, v103
	v_exp_f32_e32 v104, v104
	v_exp_f32_e32 v105, v105
	v_exp_f32_e32 v70, v70
	v_exp_f32_e32 v71, v71
	v_exp_f32_e32 v72, v72
	v_exp_f32_e32 v73, v73
	v_exp_f32_e32 v36, v36
	v_exp_f32_e32 v37, v37
	v_exp_f32_e32 v38, v38
	v_exp_f32_e32 v39, v39
	v_exp_f32_e32 v4, v4
	v_exp_f32_e32 v5, v5
	v_exp_f32_e32 v6, v6
	v_exp_f32_e32 v7, v7
	v_add_f32_e32 v102, 1.0, v102
	v_add_f32_e32 v103, 1.0, v103
	v_add_f32_e32 v104, 1.0, v104
	v_add_f32_e32 v105, 1.0, v105
	v_add_f32_e32 v70, 1.0, v70
	v_add_f32_e32 v71, 1.0, v71
	v_add_f32_e32 v72, 1.0, v72
	v_add_f32_e32 v73, 1.0, v73
	v_add_f32_e32 v36, 1.0, v36
	v_add_f32_e32 v37, 1.0, v37
	v_add_f32_e32 v38, 1.0, v38
	v_add_f32_e32 v39, 1.0, v39
	v_add_f32_e32 v4, 1.0, v4
	v_add_f32_e32 v5, 1.0, v5
	v_add_f32_e32 v6, 1.0, v6
	v_add_f32_e32 v7, 1.0, v7
	v_rcp_f32_e32 v102, v102
	v_rcp_f32_e32 v103, v103
	v_rcp_f32_e32 v104, v104
	v_rcp_f32_e32 v105, v105
	v_rcp_f32_e32 v70, v70
	v_rcp_f32_e32 v71, v71
	v_rcp_f32_e32 v72, v72
	v_rcp_f32_e32 v73, v73
	v_rcp_f32_e32 v36, v36
	v_rcp_f32_e32 v37, v37
	v_rcp_f32_e32 v38, v38
	v_rcp_f32_e32 v39, v39
	v_rcp_f32_e32 v4, v4
	v_rcp_f32_e32 v5, v5
	v_rcp_f32_e32 v6, v6
	v_rcp_f32_e32 v7, v7
	v_cvt_pk_bf16_f32 v102, v102, v103
	v_cvt_pk_bf16_f32 v103, v104, v105
	v_cvt_pk_bf16_f32 v104, v70, v71
	v_cvt_pk_bf16_f32 v105, v72, v73
	v_cvt_pk_bf16_f32 v36, v36, v37
	v_cvt_pk_bf16_f32 v37, v38, v39
	v_cvt_pk_bf16_f32 v38, v4, v5
	v_cvt_pk_bf16_f32 v39, v6, v7
	s_nop 1
	v_permlane16_swap_b32_e32 v102, v104
	v_permlane16_swap_b32_e32 v103, v105
	v_permlane16_swap_b32_e32 v36, v38
	v_permlane16_swap_b32_e32 v37, v39
	global_store_dwordx4 v[246:247], v[102:105], off
	global_store_dwordx4 v[246:247], v[36:39], off offset:64
	v_add_co_u32_e32 v246, vcc, 0x46000, v246
	s_nop 1
	v_addc_co_u32_e32 v247, vcc, 0, v247, vcc
	v_mul_f32_e32 v98, 0xbfb8aa3b, v98
	v_mul_f32_e32 v99, 0xbfb8aa3b, v99
	v_mul_f32_e32 v100, 0xbfb8aa3b, v100
	v_mul_f32_e32 v101, 0xbfb8aa3b, v101
	v_mul_f32_e32 v66, 0xbfb8aa3b, v66
	v_mul_f32_e32 v67, 0xbfb8aa3b, v67
	v_mul_f32_e32 v68, 0xbfb8aa3b, v68
	v_mul_f32_e32 v69, 0xbfb8aa3b, v69
	v_mul_f32_e32 v28, 0xbfb8aa3b, v28
	v_mul_f32_e32 v29, 0xbfb8aa3b, v29
	v_mul_f32_e32 v30, 0xbfb8aa3b, v30
	v_mul_f32_e32 v31, 0xbfb8aa3b, v31
	v_mul_f32_e32 v0, 0xbfb8aa3b, v0
	v_mul_f32_e32 v1, 0xbfb8aa3b, v1
	v_mul_f32_e32 v2, 0xbfb8aa3b, v2
	v_mul_f32_e32 v3, 0xbfb8aa3b, v3
	v_exp_f32_e32 v98, v98
	v_exp_f32_e32 v99, v99
	v_exp_f32_e32 v100, v100
	v_exp_f32_e32 v101, v101
	v_exp_f32_e32 v66, v66
	v_exp_f32_e32 v67, v67
	v_exp_f32_e32 v68, v68
	v_exp_f32_e32 v69, v69
	v_exp_f32_e32 v28, v28
	v_exp_f32_e32 v29, v29
	v_exp_f32_e32 v30, v30
	v_exp_f32_e32 v31, v31
	v_exp_f32_e32 v0, v0
	v_exp_f32_e32 v1, v1
	v_exp_f32_e32 v2, v2
	v_exp_f32_e32 v3, v3
	v_add_f32_e32 v98, 1.0, v98
	v_add_f32_e32 v99, 1.0, v99
	v_add_f32_e32 v100, 1.0, v100
	v_add_f32_e32 v101, 1.0, v101
	v_add_f32_e32 v66, 1.0, v66
	v_add_f32_e32 v67, 1.0, v67
	v_add_f32_e32 v68, 1.0, v68
	v_add_f32_e32 v69, 1.0, v69
	v_add_f32_e32 v28, 1.0, v28
	v_add_f32_e32 v29, 1.0, v29
	v_add_f32_e32 v30, 1.0, v30
	v_add_f32_e32 v31, 1.0, v31
	v_add_f32_e32 v0, 1.0, v0
	v_add_f32_e32 v1, 1.0, v1
	v_add_f32_e32 v2, 1.0, v2
	v_add_f32_e32 v3, 1.0, v3
	v_rcp_f32_e32 v98, v98
	v_rcp_f32_e32 v99, v99
	v_rcp_f32_e32 v100, v100
	v_rcp_f32_e32 v101, v101
	v_rcp_f32_e32 v66, v66
	v_rcp_f32_e32 v67, v67
	v_rcp_f32_e32 v68, v68
	v_rcp_f32_e32 v69, v69
	v_rcp_f32_e32 v28, v28
	v_rcp_f32_e32 v29, v29
	v_rcp_f32_e32 v30, v30
	v_rcp_f32_e32 v31, v31
	v_rcp_f32_e32 v0, v0
	v_rcp_f32_e32 v1, v1
	v_rcp_f32_e32 v2, v2
	v_rcp_f32_e32 v3, v3
	v_cvt_pk_bf16_f32 v98, v98, v99
	v_cvt_pk_bf16_f32 v99, v100, v101
	v_cvt_pk_bf16_f32 v100, v66, v67
	v_cvt_pk_bf16_f32 v101, v68, v69
	v_cvt_pk_bf16_f32 v28, v28, v29
	v_cvt_pk_bf16_f32 v29, v30, v31
	v_cvt_pk_bf16_f32 v30, v0, v1
	v_cvt_pk_bf16_f32 v31, v2, v3
	s_nop 1
	v_permlane16_swap_b32_e32 v98, v100
	v_permlane16_swap_b32_e32 v99, v101
	v_permlane16_swap_b32_e32 v28, v30
	v_permlane16_swap_b32_e32 v29, v31
	global_store_dwordx4 v[246:247], v[98:101], off
	global_store_dwordx4 v[246:247], v[28:31], off offset:64
	s_branch .Le1_done
.Le1_plain:
	v_cvt_pk_bf16_f32 v126, v126, v127
	v_cvt_pk_bf16_f32 v127, v128, v129
	v_cvt_pk_bf16_f32 v128, v94, v95
	v_cvt_pk_bf16_f32 v129, v96, v97
	v_cvt_pk_bf16_f32 v60, v60, v61
	v_cvt_pk_bf16_f32 v61, v62, v63
	v_cvt_pk_bf16_f32 v62, v32, v33
	v_cvt_pk_bf16_f32 v63, v34, v35
	s_nop 1
	v_permlane16_swap_b32_e32 v126, v128
	v_permlane16_swap_b32_e32 v127, v129
	v_permlane16_swap_b32_e32 v60, v62
	v_permlane16_swap_b32_e32 v61, v63
	global_store_dwordx4 v[246:247], v[126:129], off
	global_store_dwordx4 v[246:247], v[60:63], off offset:64
	v_add_co_u32_e32 v246, vcc, 0x46000, v246
	s_nop 1
	v_addc_co_u32_e32 v247, vcc, 0, v247, vcc
	v_cvt_pk_bf16_f32 v122, v122, v123
	v_cvt_pk_bf16_f32 v123, v124, v125
	v_cvt_pk_bf16_f32 v124, v90, v91
	v_cvt_pk_bf16_f32 v125, v92, v93
	v_cvt_pk_bf16_f32 v56, v56, v57
	v_cvt_pk_bf16_f32 v57, v58, v59
	v_cvt_pk_bf16_f32 v58, v24, v25
	v_cvt_pk_bf16_f32 v59, v26, v27
	s_nop 1
	v_permlane16_swap_b32_e32 v122, v124
	v_permlane16_swap_b32_e32 v123, v125
	v_permlane16_swap_b32_e32 v56, v58
	v_permlane16_swap_b32_e32 v57, v59
	global_store_dwordx4 v[246:247], v[122:125], off
	global_store_dwordx4 v[246:247], v[56:59], off offset:64
	v_add_co_u32_e32 v246, vcc, 0x46000, v246
	s_nop 1
	v_addc_co_u32_e32 v247, vcc, 0, v247, vcc
	v_cvt_pk_bf16_f32 v118, v118, v119
	v_cvt_pk_bf16_f32 v119, v120, v121
	v_cvt_pk_bf16_f32 v120, v86, v87
	v_cvt_pk_bf16_f32 v121, v88, v89
	v_cvt_pk_bf16_f32 v52, v52, v53
	v_cvt_pk_bf16_f32 v53, v54, v55
	v_cvt_pk_bf16_f32 v54, v20, v21
	v_cvt_pk_bf16_f32 v55, v22, v23
	s_nop 1
	v_permlane16_swap_b32_e32 v118, v120
	v_permlane16_swap_b32_e32 v119, v121
	v_permlane16_swap_b32_e32 v52, v54
	v_permlane16_swap_b32_e32 v53, v55
	global_store_dwordx4 v[246:247], v[118:121], off
	global_store_dwordx4 v[246:247], v[52:55], off offset:64
	v_add_co_u32_e32 v246, vcc, 0x46000, v246
	s_nop 1
	v_addc_co_u32_e32 v247, vcc, 0, v247, vcc
	v_cvt_pk_bf16_f32 v114, v114, v115
	v_cvt_pk_bf16_f32 v115, v116, v117
	v_cvt_pk_bf16_f32 v116, v82, v83
	v_cvt_pk_bf16_f32 v117, v84, v85
	v_cvt_pk_bf16_f32 v48, v48, v49
	v_cvt_pk_bf16_f32 v49, v50, v51
	v_cvt_pk_bf16_f32 v50, v16, v17
	v_cvt_pk_bf16_f32 v51, v18, v19
	s_nop 1
	v_permlane16_swap_b32_e32 v114, v116
	v_permlane16_swap_b32_e32 v115, v117
	v_permlane16_swap_b32_e32 v48, v50
	v_permlane16_swap_b32_e32 v49, v51
	global_store_dwordx4 v[246:247], v[114:117], off
	global_store_dwordx4 v[246:247], v[48:51], off offset:64
	v_add_co_u32_e32 v246, vcc, 0x46000, v246
	s_nop 1
	v_addc_co_u32_e32 v247, vcc, 0, v247, vcc
	v_cvt_pk_bf16_f32 v110, v110, v111
	v_cvt_pk_bf16_f32 v111, v112, v113
	v_cvt_pk_bf16_f32 v112, v78, v79
	v_cvt_pk_bf16_f32 v113, v80, v81
	v_cvt_pk_bf16_f32 v44, v44, v45
	v_cvt_pk_bf16_f32 v45, v46, v47
	v_cvt_pk_bf16_f32 v46, v12, v13
	v_cvt_pk_bf16_f32 v47, v14, v15
	s_nop 1
	v_permlane16_swap_b32_e32 v110, v112
	v_permlane16_swap_b32_e32 v111, v113
	v_permlane16_swap_b32_e32 v44, v46
	v_permlane16_swap_b32_e32 v45, v47
	global_store_dwordx4 v[246:247], v[110:113], off
	global_store_dwordx4 v[246:247], v[44:47], off offset:64
	v_add_co_u32_e32 v246, vcc, 0x46000, v246
	s_nop 1
	v_addc_co_u32_e32 v247, vcc, 0, v247, vcc
	v_cvt_pk_bf16_f32 v106, v106, v107
	v_cvt_pk_bf16_f32 v107, v108, v109
	v_cvt_pk_bf16_f32 v108, v74, v75
	v_cvt_pk_bf16_f32 v109, v76, v77
	v_cvt_pk_bf16_f32 v40, v40, v41
	v_cvt_pk_bf16_f32 v41, v42, v43
	v_cvt_pk_bf16_f32 v42, v8, v9
	v_cvt_pk_bf16_f32 v43, v10, v11
	s_nop 1
	v_permlane16_swap_b32_e32 v106, v108
	v_permlane16_swap_b32_e32 v107, v109
	v_permlane16_swap_b32_e32 v40, v42
	v_permlane16_swap_b32_e32 v41, v43
	global_store_dwordx4 v[246:247], v[106:109], off
	global_store_dwordx4 v[246:247], v[40:43], off offset:64
	v_add_co_u32_e32 v246, vcc, 0x46000, v246
	s_nop 1
	v_addc_co_u32_e32 v247, vcc, 0, v247, vcc
	v_cvt_pk_bf16_f32 v102, v102, v103
	v_cvt_pk_bf16_f32 v103, v104, v105
	v_cvt_pk_bf16_f32 v104, v70, v71
	v_cvt_pk_bf16_f32 v105, v72, v73
	v_cvt_pk_bf16_f32 v36, v36, v37
	v_cvt_pk_bf16_f32 v37, v38, v39
	v_cvt_pk_bf16_f32 v38, v4, v5
	v_cvt_pk_bf16_f32 v39, v6, v7
	s_nop 1
	v_permlane16_swap_b32_e32 v102, v104
	v_permlane16_swap_b32_e32 v103, v105
	v_permlane16_swap_b32_e32 v36, v38
	v_permlane16_swap_b32_e32 v37, v39
	global_store_dwordx4 v[246:247], v[102:105], off
	global_store_dwordx4 v[246:247], v[36:39], off offset:64
	v_add_co_u32_e32 v246, vcc, 0x46000, v246
	s_nop 1
	v_addc_co_u32_e32 v247, vcc, 0, v247, vcc
	v_cvt_pk_bf16_f32 v98, v98, v99
	v_cvt_pk_bf16_f32 v99, v100, v101
	v_cvt_pk_bf16_f32 v100, v66, v67
	v_cvt_pk_bf16_f32 v101, v68, v69
	v_cvt_pk_bf16_f32 v28, v28, v29
	v_cvt_pk_bf16_f32 v29, v30, v31
	v_cvt_pk_bf16_f32 v30, v0, v1
	v_cvt_pk_bf16_f32 v31, v2, v3
	s_nop 1
	v_permlane16_swap_b32_e32 v98, v100
	v_permlane16_swap_b32_e32 v99, v101
	v_permlane16_swap_b32_e32 v28, v30
	v_permlane16_swap_b32_e32 v29, v31
	global_store_dwordx4 v[246:247], v[98:101], off
	global_store_dwordx4 v[246:247], v[28:31], off offset:64
	s_branch .Le1_done
.Le1_rot:
	s_mov_b32 s27, s26
	v_mbcnt_hi_u32_b32 v253, -1, v167
	v_xor_b32_e32 v253, 32, v253
	v_lshlrev_b32_e32 v253, 2, v253
	v_and_b32_e32 v252, 32, v166
	v_xor_b32_e32 v252, 32, v252
	v_lshlrev_b32_e32 v252, 26, v252
	v_lshlrev_b32_e32 v254, 6, v248
	v_and_b32_e32 v255, 16, v166
	v_or_b32_e32 v254, v254, v255
	v_mov_b32_e32 v255, 0
	v_lshl_add_u64 v[254:255], v[254:255], 0, s[64:65]
	global_load_dwordx4 v[130:133], v[254:255], off offset:0
	global_load_dwordx4 v[134:137], v[254:255], off offset:32
	global_load_dwordx4 v[138:141], v[254:255], off offset:1024
	global_load_dwordx4 v[142:145], v[254:255], off offset:1056
	global_load_dwordx4 v[146:149], v[254:255], off offset:2048
	global_load_dwordx4 v[150:153], v[254:255], off offset:2080
	global_load_dwordx4 v[202:205], v[254:255], off offset:3072
	global_load_dwordx4 v[206:209], v[254:255], off offset:3104
	v_add_co_u32_e32 v254, vcc, 0x1000, v254
	s_nop 1
	v_addc_co_u32_e32 v255, vcc, 0, v255, vcc
	ds_bpermute_b32 v248, v253, v126
	ds_bpermute_b32 v249, v253, v127
	ds_bpermute_b32 v250, v253, v128
	ds_bpermute_b32 v251, v253, v129
	s_waitcnt vmcnt(6) lgkmcnt(0)
	v_pk_mul_f32 v[248:249], v[134:135], v[248:249]
	v_pk_mul_f32 v[250:251], v[136:137], v[250:251]
	v_xor_b32_e32 v248, v252, v248
	v_xor_b32_e32 v249, v252, v249
	v_xor_b32_e32 v250, v252, v250
	v_xor_b32_e32 v251, v252, v251
	v_pk_fma_f32 v[126:127], v[126:127], v[130:131], v[248:249]
	v_pk_fma_f32 v[128:129], v[128:129], v[132:133], v[250:251]
	v_pk_mul_f32 v[126:127], s[26:27], v[126:127]
	v_pk_mul_f32 v[128:129], s[26:27], v[128:129]
	v_pk_mul_f32 v[94:95], s[26:27], v[94:95]
	v_pk_mul_f32 v[96:97], s[26:27], v[96:97]
	v_pk_mul_f32 v[60:61], s[26:27], v[60:61]
	v_pk_mul_f32 v[62:63], s[26:27], v[62:63]
	v_pk_mul_f32 v[32:33], s[26:27], v[32:33]
	v_pk_mul_f32 v[34:35], s[26:27], v[34:35]
	v_cvt_pk_bf16_f32 v126, v126, v127
	v_cvt_pk_bf16_f32 v127, v128, v129
	v_cvt_pk_bf16_f32 v128, v94, v95
	v_cvt_pk_bf16_f32 v129, v96, v97
	v_cvt_pk_bf16_f32 v60, v60, v61
	v_cvt_pk_bf16_f32 v61, v62, v63
	v_cvt_pk_bf16_f32 v62, v32, v33
	v_cvt_pk_bf16_f32 v63, v34, v35
	s_nop 1
	v_permlane16_swap_b32_e32 v126, v128
	v_permlane16_swap_b32_e32 v127, v129
	v_permlane16_swap_b32_e32 v60, v62
	v_permlane16_swap_b32_e32 v61, v63
	global_store_dwordx4 v[246:247], v[126:129], off
	global_store_dwordx4 v[246:247], v[60:63], off offset:64
	v_add_co_u32_e32 v246, vcc, 0x46000, v246
	s_nop 1
	v_addc_co_u32_e32 v247, vcc, 0, v247, vcc
	ds_bpermute_b32 v248, v253, v122
	ds_bpermute_b32 v249, v253, v123
	ds_bpermute_b32 v250, v253, v124
	ds_bpermute_b32 v251, v253, v125
	s_waitcnt vmcnt(6) lgkmcnt(0)
	v_pk_mul_f32 v[248:249], v[142:143], v[248:249]
	v_pk_mul_f32 v[250:251], v[144:145], v[250:251]
	v_xor_b32_e32 v248, v252, v248
	v_xor_b32_e32 v249, v252, v249
	v_xor_b32_e32 v250, v252, v250
	v_xor_b32_e32 v251, v252, v251
	v_pk_fma_f32 v[122:123], v[122:123], v[138:139], v[248:249]
	v_pk_fma_f32 v[124:125], v[124:125], v[140:141], v[250:251]
	v_pk_mul_f32 v[122:123], s[26:27], v[122:123]
	v_pk_mul_f32 v[124:125], s[26:27], v[124:125]
	v_pk_mul_f32 v[90:91], s[26:27], v[90:91]
	v_pk_mul_f32 v[92:93], s[26:27], v[92:93]
	v_pk_mul_f32 v[56:57], s[26:27], v[56:57]
	v_pk_mul_f32 v[58:59], s[26:27], v[58:59]
	v_pk_mul_f32 v[24:25], s[26:27], v[24:25]
	v_pk_mul_f32 v[26:27], s[26:27], v[26:27]
	v_cvt_pk_bf16_f32 v122, v122, v123
	v_cvt_pk_bf16_f32 v123, v124, v125
	v_cvt_pk_bf16_f32 v124, v90, v91
	v_cvt_pk_bf16_f32 v125, v92, v93
	v_cvt_pk_bf16_f32 v56, v56, v57
	v_cvt_pk_bf16_f32 v57, v58, v59
	v_cvt_pk_bf16_f32 v58, v24, v25
	v_cvt_pk_bf16_f32 v59, v26, v27
	s_nop 1
	v_permlane16_swap_b32_e32 v122, v124
	v_permlane16_swap_b32_e32 v123, v125
	v_permlane16_swap_b32_e32 v56, v58
	v_permlane16_swap_b32_e32 v57, v59
	global_store_dwordx4 v[246:247], v[122:125], off
	global_store_dwordx4 v[246:247], v[56:59], off offset:64
	v_add_co_u32_e32 v246, vcc, 0x46000, v246
	s_nop 1
	v_addc_co_u32_e32 v247, vcc, 0, v247, vcc
	global_load_dwordx4 v[130:133], v[254:255], off offset:0
	global_load_dwordx4 v[134:137], v[254:255], off offset:32
	global_load_dwordx4 v[138:141], v[254:255], off offset:1024
	global_load_dwordx4 v[142:145], v[254:255], off offset:1056
	ds_bpermute_b32 v248, v253, v118
	ds_bpermute_b32 v249, v253, v119
	ds_bpermute_b32 v250, v253, v120
	ds_bpermute_b32 v251, v253, v121
	s_waitcnt vmcnt(10) lgkmcnt(0)
	v_pk_mul_f32 v[248:249], v[150:151], v[248:249]
	v_pk_mul_f32 v[250:251], v[152:153], v[250:251]
	v_xor_b32_e32 v248, v252, v248
	v_xor_b32_e32 v249, v252, v249
	v_xor_b32_e32 v250, v252, v250
	v_xor_b32_e32 v251, v252, v251
	v_pk_fma_f32 v[118:119], v[118:119], v[146:147], v[248:249]
	v_pk_fma_f32 v[120:121], v[120:121], v[148:149], v[250:251]
	v_pk_mul_f32 v[118:119], s[26:27], v[118:119]
	v_pk_mul_f32 v[120:121], s[26:27], v[120:121]
	v_pk_mul_f32 v[86:87], s[26:27], v[86:87]
	v_pk_mul_f32 v[88:89], s[26:27], v[88:89]
	v_pk_mul_f32 v[52:53], s[26:27], v[52:53]
	v_pk_mul_f32 v[54:55], s[26:27], v[54:55]
	v_pk_mul_f32 v[20:21], s[26:27], v[20:21]
	v_pk_mul_f32 v[22:23], s[26:27], v[22:23]
	v_cvt_pk_bf16_f32 v118, v118, v119
	v_cvt_pk_bf16_f32 v119, v120, v121
	v_cvt_pk_bf16_f32 v120, v86, v87
	v_cvt_pk_bf16_f32 v121, v88, v89
	v_cvt_pk_bf16_f32 v52, v52, v53
	v_cvt_pk_bf16_f32 v53, v54, v55
	v_cvt_pk_bf16_f32 v54, v20, v21
	v_cvt_pk_bf16_f32 v55, v22, v23
	s_nop 1
	v_permlane16_swap_b32_e32 v118, v120
	v_permlane16_swap_b32_e32 v119, v121
	v_permlane16_swap_b32_e32 v52, v54
	v_permlane16_swap_b32_e32 v53, v55
	global_store_dwordx4 v[246:247], v[118:121], off
	global_store_dwordx4 v[246:247], v[52:55], off offset:64
	v_add_co_u32_e32 v246, vcc, 0x46000, v246
	s_nop 1
	v_addc_co_u32_e32 v247, vcc, 0, v247, vcc
	ds_bpermute_b32 v248, v253, v114
	ds_bpermute_b32 v249, v253, v115
	ds_bpermute_b32 v250, v253, v116
	ds_bpermute_b32 v251, v253, v117
	s_waitcnt vmcnt(10) lgkmcnt(0)
	v_pk_mul_f32 v[248:249], v[206:207], v[248:249]
	v_pk_mul_f32 v[250:251], v[208:209], v[250:251]
	v_xor_b32_e32 v248, v252, v248
	v_xor_b32_e32 v249, v252, v249
	v_xor_b32_e32 v250, v252, v250
	v_xor_b32_e32 v251, v252, v251
	v_pk_fma_f32 v[114:115], v[114:115], v[202:203], v[248:249]
	v_pk_fma_f32 v[116:117], v[116:117], v[204:205], v[250:251]
	v_pk_mul_f32 v[114:115], s[26:27], v[114:115]
	v_pk_mul_f32 v[116:117], s[26:27], v[116:117]
	v_pk_mul_f32 v[82:83], s[26:27], v[82:83]
	v_pk_mul_f32 v[84:85], s[26:27], v[84:85]
	v_pk_mul_f32 v[48:49], s[26:27], v[48:49]
	v_pk_mul_f32 v[50:51], s[26:27], v[50:51]
	v_pk_mul_f32 v[16:17], s[26:27], v[16:17]
	v_pk_mul_f32 v[18:19], s[26:27], v[18:19]
	v_cvt_pk_bf16_f32 v114, v114, v115
	v_cvt_pk_bf16_f32 v115, v116, v117
	v_cvt_pk_bf16_f32 v116, v82, v83
	v_cvt_pk_bf16_f32 v117, v84, v85
	v_cvt_pk_bf16_f32 v48, v48, v49
	v_cvt_pk_bf16_f32 v49, v50, v51
	v_cvt_pk_bf16_f32 v50, v16, v17
	v_cvt_pk_bf16_f32 v51, v18, v19
	s_nop 1
	v_permlane16_swap_b32_e32 v114, v116
	v_permlane16_swap_b32_e32 v115, v117
	v_permlane16_swap_b32_e32 v48, v50
	v_permlane16_swap_b32_e32 v49, v51
	global_store_dwordx4 v[246:247], v[114:117], off
	global_store_dwordx4 v[246:247], v[48:51], off offset:64
	v_add_co_u32_e32 v246, vcc, 0x46000, v246
	s_nop 1
	v_addc_co_u32_e32 v247, vcc, 0, v247, vcc
	global_load_dwordx4 v[146:149], v[254:255], off offset:2048
	global_load_dwordx4 v[150:153], v[254:255], off offset:2080
	global_load_dwordx4 v[202:205], v[254:255], off offset:3072
	global_load_dwordx4 v[206:209], v[254:255], off offset:3104
	ds_bpermute_b32 v248, v253, v110
	ds_bpermute_b32 v249, v253, v111
	ds_bpermute_b32 v250, v253, v112
	ds_bpermute_b32 v251, v253, v113
	s_waitcnt vmcnt(10) lgkmcnt(0)
	v_pk_mul_f32 v[248:249], v[134:135], v[248:249]
	v_pk_mul_f32 v[250:251], v[136:137], v[250:251]
	v_xor_b32_e32 v248, v252, v248
	v_xor_b32_e32 v249, v252, v249
	v_xor_b32_e32 v250, v252, v250
	v_xor_b32_e32 v251, v252, v251
	v_pk_fma_f32 v[110:111], v[110:111], v[130:131], v[248:249]
	v_pk_fma_f32 v[112:113], v[112:113], v[132:133], v[250:251]
	v_pk_mul_f32 v[110:111], s[26:27], v[110:111]
	v_pk_mul_f32 v[112:113], s[26:27], v[112:113]
	v_pk_mul_f32 v[78:79], s[26:27], v[78:79]
	v_pk_mul_f32 v[80:81], s[26:27], v[80:81]
	v_pk_mul_f32 v[44:45], s[26:27], v[44:45]
	v_pk_mul_f32 v[46:47], s[26:27], v[46:47]
	v_pk_mul_f32 v[12:13], s[26:27], v[12:13]
	v_pk_mul_f32 v[14:15], s[26:27], v[14:15]
	v_cvt_pk_bf16_f32 v110, v110, v111
	v_cvt_pk_bf16_f32 v111, v112, v113
	v_cvt_pk_bf16_f32 v112, v78, v79
	v_cvt_pk_bf16_f32 v113, v80, v81
	v_cvt_pk_bf16_f32 v44, v44, v45
	v_cvt_pk_bf16_f32 v45, v46, v47
	v_cvt_pk_bf16_f32 v46, v12, v13
	v_cvt_pk_bf16_f32 v47, v14, v15
	s_nop 1
	v_permlane16_swap_b32_e32 v110, v112
	v_permlane16_swap_b32_e32 v111, v113
	v_permlane16_swap_b32_e32 v44, v46
	v_permlane16_swap_b32_e32 v45, v47
	global_store_dwordx4 v[246:247], v[110:113], off
	global_store_dwordx4 v[246:247], v[44:47], off offset:64
	v_add_co_u32_e32 v246, vcc, 0x46000, v246
	s_nop 1
	v_addc_co_u32_e32 v247, vcc, 0, v247, vcc
	ds_bpermute_b32 v248, v253, v106
	ds_bpermute_b32 v249, v253, v107
	ds_bpermute_b32 v250, v253, v108
	ds_bpermute_b32 v251, v253, v109
	s_waitcnt vmcnt(10) lgkmcnt(0)
	v_pk_mul_f32 v[248:249], v[142:143], v[248:249]
	v_pk_mul_f32 v[250:251], v[144:145], v[250:251]
	v_xor_b32_e32 v248, v252, v248
	v_xor_b32_e32 v249, v252, v249
	v_xor_b32_e32 v250, v252, v250
	v_xor_b32_e32 v251, v252, v251
	v_pk_fma_f32 v[106:107], v[106:107], v[138:139], v[248:249]
	v_pk_fma_f32 v[108:109], v[108:109], v[140:141], v[250:251]
	v_pk_mul_f32 v[106:107], s[26:27], v[106:107]
	v_pk_mul_f32 v[108:109], s[26:27], v[108:109]
	v_pk_mul_f32 v[74:75], s[26:27], v[74:75]
	v_pk_mul_f32 v[76:77], s[26:27], v[76:77]
	v_pk_mul_f32 v[40:41], s[26:27], v[40:41]
	v_pk_mul_f32 v[42:43], s[26:27], v[42:43]
	v_pk_mul_f32 v[8:9], s[26:27], v[8:9]
	v_pk_mul_f32 v[10:11], s[26:27], v[10:11]
	v_cvt_pk_bf16_f32 v106, v106, v107
	v_cvt_pk_bf16_f32 v107, v108, v109
	v_cvt_pk_bf16_f32 v108, v74, v75
	v_cvt_pk_bf16_f32 v109, v76, v77
	v_cvt_pk_bf16_f32 v40, v40, v41
	v_cvt_pk_bf16_f32 v41, v42, v43
	v_cvt_pk_bf16_f32 v42, v8, v9
	v_cvt_pk_bf16_f32 v43, v10, v11
	s_nop 1
	v_permlane16_swap_b32_e32 v106, v108
	v_permlane16_swap_b32_e32 v107, v109
	v_permlane16_swap_b32_e32 v40, v42
	v_permlane16_swap_b32_e32 v41, v43
	global_store_dwordx4 v[246:247], v[106:109], off
	global_store_dwordx4 v[246:247], v[40:43], off offset:64
	v_add_co_u32_e32 v246, vcc, 0x46000, v246
	s_nop 1
	v_addc_co_u32_e32 v247, vcc, 0, v247, vcc
	ds_bpermute_b32 v248, v253, v102
	ds_bpermute_b32 v249, v253, v103
	ds_bpermute_b32 v250, v253, v104
	ds_bpermute_b32 v251, v253, v105
	s_waitcnt vmcnt(6) lgkmcnt(0)
	v_pk_mul_f32 v[248:249], v[150:151], v[248:249]
	v_pk_mul_f32 v[250:251], v[152:153], v[250:251]
	v_xor_b32_e32 v248, v252, v248
	v_xor_b32_e32 v249, v252, v249
	v_xor_b32_e32 v250, v252, v250
	v_xor_b32_e32 v251, v252, v251
	v_pk_fma_f32 v[102:103], v[102:103], v[146:147], v[248:249]
	v_pk_fma_f32 v[104:105], v[104:105], v[148:149], v[250:251]
	v_pk_mul_f32 v[102:103], s[26:27], v[102:103]
	v_pk_mul_f32 v[104:105], s[26:27], v[104:105]
	v_pk_mul_f32 v[70:71], s[26:27], v[70:71]
	v_pk_mul_f32 v[72:73], s[26:27], v[72:73]
	v_pk_mul_f32 v[36:37], s[26:27], v[36:37]
	v_pk_mul_f32 v[38:39], s[26:27], v[38:39]
	v_pk_mul_f32 v[4:5], s[26:27], v[4:5]
	v_pk_mul_f32 v[6:7], s[26:27], v[6:7]
	v_cvt_pk_bf16_f32 v102, v102, v103
	v_cvt_pk_bf16_f32 v103, v104, v105
	v_cvt_pk_bf16_f32 v104, v70, v71
	v_cvt_pk_bf16_f32 v105, v72, v73
	v_cvt_pk_bf16_f32 v36, v36, v37
	v_cvt_pk_bf16_f32 v37, v38, v39
	v_cvt_pk_bf16_f32 v38, v4, v5
	v_cvt_pk_bf16_f32 v39, v6, v7
	s_nop 1
	v_permlane16_swap_b32_e32 v102, v104
	v_permlane16_swap_b32_e32 v103, v105
	v_permlane16_swap_b32_e32 v36, v38
	v_permlane16_swap_b32_e32 v37, v39
	global_store_dwordx4 v[246:247], v[102:105], off
	global_store_dwordx4 v[246:247], v[36:39], off offset:64
	v_add_co_u32_e32 v246, vcc, 0x46000, v246
	s_nop 1
	v_addc_co_u32_e32 v247, vcc, 0, v247, vcc
	ds_bpermute_b32 v248, v253, v98
	ds_bpermute_b32 v249, v253, v99
	ds_bpermute_b32 v250, v253, v100
	ds_bpermute_b32 v251, v253, v101
	s_waitcnt vmcnt(6) lgkmcnt(0)
	v_pk_mul_f32 v[248:249], v[206:207], v[248:249]
	v_pk_mul_f32 v[250:251], v[208:209], v[250:251]
	v_xor_b32_e32 v248, v252, v248
	v_xor_b32_e32 v249, v252, v249
	v_xor_b32_e32 v250, v252, v250
	v_xor_b32_e32 v251, v252, v251
	v_pk_fma_f32 v[98:99], v[98:99], v[202:203], v[248:249]
	v_pk_fma_f32 v[100:101], v[100:101], v[204:205], v[250:251]
	v_pk_mul_f32 v[98:99], s[26:27], v[98:99]
	v_pk_mul_f32 v[100:101], s[26:27], v[100:101]
	v_pk_mul_f32 v[66:67], s[26:27], v[66:67]
	v_pk_mul_f32 v[68:69], s[26:27], v[68:69]
	v_pk_mul_f32 v[28:29], s[26:27], v[28:29]
	v_pk_mul_f32 v[30:31], s[26:27], v[30:31]
	v_pk_mul_f32 v[0:1], s[26:27], v[0:1]
	v_pk_mul_f32 v[2:3], s[26:27], v[2:3]
	v_cvt_pk_bf16_f32 v98, v98, v99
	v_cvt_pk_bf16_f32 v99, v100, v101
	v_cvt_pk_bf16_f32 v100, v66, v67
	v_cvt_pk_bf16_f32 v101, v68, v69
	v_cvt_pk_bf16_f32 v28, v28, v29
	v_cvt_pk_bf16_f32 v29, v30, v31
	v_cvt_pk_bf16_f32 v30, v0, v1
	v_cvt_pk_bf16_f32 v31, v2, v3
	s_nop 1
	v_permlane16_swap_b32_e32 v98, v100
	v_permlane16_swap_b32_e32 v99, v101
	v_permlane16_swap_b32_e32 v28, v30
	v_permlane16_swap_b32_e32 v29, v31
	global_store_dwordx4 v[246:247], v[98:101], off
	global_store_dwordx4 v[246:247], v[28:31], off offset:64
.Le1_done:
	s_add_i32 s78, s78, 1
	s_andn2_b64 vcc, exec, s[76:77]
	s_cbranch_vccz .LBB0_788
	s_branch .LBB0_615

.LBB0_1636:
	s_add_i32 s64, s64, 1
	s_mul_hi_i32 s1, s24, 0x2c0000
	s_mul_i32 s24, s24, 0x2c0000
	s_add_u32 s24, s18, s24
	s_addc_u32 s25, s19, s1
	s_lshl_b32 s0, s0, 8
	s_ashr_i32 s1, s0, 31
	s_lshl_b64 s[0:1], s[0:1], 1
	s_add_u32 s0, s24, s0
	s_mov_b32 s24, 0x7fff80
	s_addc_u32 s1, s25, s1
	v_mov_b32_e32 v248, v166
	v_and_b32_e32 v249, 15, v248
	v_lshrrev_b32_e32 v250, 1, v248
	v_and_b32_e32 v251, 0xc0, v248
	v_and_or_b32 v249, v250, s24, v249
	v_and_b32_e32 v250, 16, v248
	v_lshrrev_b32_e32 v248, 2, v248
	v_and_b32_e32 v248, 8, v248
	v_or_b32_e32 v248, v248, v250
	v_mul_u32_u24_e32 v250, 0x1600, v249
	v_or3_b32 v248, v248, v251, v250
	v_mov_b32_e32 v249, 0
	v_lshl_add_u64 v[246:247], v[248:249], 1, s[0:1]
	v_cvt_pk_bf16_f32 v126, v126, v127
	v_cvt_pk_bf16_f32 v127, v128, v129
	v_cvt_pk_bf16_f32 v128, v122, v123
	v_cvt_pk_bf16_f32 v129, v124, v125
	v_cvt_pk_bf16_f32 v118, v118, v119
	v_cvt_pk_bf16_f32 v119, v120, v121
	v_cvt_pk_bf16_f32 v120, v114, v115
	v_cvt_pk_bf16_f32 v121, v116, v117
	s_nop 1
	v_permlane16_swap_b32_e32 v126, v128
	v_permlane16_swap_b32_e32 v127, v129
	v_permlane16_swap_b32_e32 v118, v120
	v_permlane16_swap_b32_e32 v119, v121
	global_store_dwordx4 v[246:247], v[126:129], off
	global_store_dwordx4 v[246:247], v[118:121], off offset:64
	v_add_co_u32_e32 v246, vcc, 0x2c000, v246
	s_nop 1
	v_addc_co_u32_e32 v247, vcc, 0, v247, vcc
	v_cvt_pk_bf16_f32 v110, v110, v111
	v_cvt_pk_bf16_f32 v111, v112, v113
	v_cvt_pk_bf16_f32 v112, v106, v107
	v_cvt_pk_bf16_f32 v113, v108, v109
	v_cvt_pk_bf16_f32 v102, v102, v103
	v_cvt_pk_bf16_f32 v103, v104, v105
	v_cvt_pk_bf16_f32 v104, v98, v99
	v_cvt_pk_bf16_f32 v105, v100, v101
	s_nop 1
	v_permlane16_swap_b32_e32 v110, v112
	v_permlane16_swap_b32_e32 v111, v113
	v_permlane16_swap_b32_e32 v102, v104
	v_permlane16_swap_b32_e32 v103, v105
	global_store_dwordx4 v[246:247], v[110:113], off
	global_store_dwordx4 v[246:247], v[102:105], off offset:64
	v_add_co_u32_e32 v246, vcc, 0x2c000, v246
	s_nop 1
	v_addc_co_u32_e32 v247, vcc, 0, v247, vcc
	v_cvt_pk_bf16_f32 v94, v94, v95
	v_cvt_pk_bf16_f32 v95, v96, v97
	v_cvt_pk_bf16_f32 v96, v90, v91
	v_cvt_pk_bf16_f32 v97, v92, v93
	v_cvt_pk_bf16_f32 v86, v86, v87
	v_cvt_pk_bf16_f32 v87, v88, v89
	v_cvt_pk_bf16_f32 v88, v82, v83
	v_cvt_pk_bf16_f32 v89, v84, v85
	s_nop 1
	v_permlane16_swap_b32_e32 v94, v96
	v_permlane16_swap_b32_e32 v95, v97
	v_permlane16_swap_b32_e32 v86, v88
	v_permlane16_swap_b32_e32 v87, v89
	global_store_dwordx4 v[246:247], v[94:97], off
	global_store_dwordx4 v[246:247], v[86:89], off offset:64
	v_add_co_u32_e32 v246, vcc, 0x2c000, v246
	s_nop 1
	v_addc_co_u32_e32 v247, vcc, 0, v247, vcc
	v_cvt_pk_bf16_f32 v78, v78, v79
	v_cvt_pk_bf16_f32 v79, v80, v81
	v_cvt_pk_bf16_f32 v80, v74, v75
	v_cvt_pk_bf16_f32 v81, v76, v77
	v_cvt_pk_bf16_f32 v70, v70, v71
	v_cvt_pk_bf16_f32 v71, v72, v73
	v_cvt_pk_bf16_f32 v72, v66, v67
	v_cvt_pk_bf16_f32 v73, v68, v69
	s_nop 1
	v_permlane16_swap_b32_e32 v78, v80
	v_permlane16_swap_b32_e32 v79, v81
	v_permlane16_swap_b32_e32 v70, v72
	v_permlane16_swap_b32_e32 v71, v73
	global_store_dwordx4 v[246:247], v[78:81], off
	global_store_dwordx4 v[246:247], v[70:73], off offset:64
	v_add_co_u32_e32 v246, vcc, 0x2c000, v246
	s_nop 1
	v_addc_co_u32_e32 v247, vcc, 0, v247, vcc
	v_cvt_pk_bf16_f32 v60, v60, v61
	v_cvt_pk_bf16_f32 v61, v62, v63
	v_cvt_pk_bf16_f32 v62, v56, v57
	v_cvt_pk_bf16_f32 v63, v58, v59
	v_cvt_pk_bf16_f32 v52, v52, v53
	v_cvt_pk_bf16_f32 v53, v54, v55
	v_cvt_pk_bf16_f32 v54, v48, v49
	v_cvt_pk_bf16_f32 v55, v50, v51
	s_nop 1
	v_permlane16_swap_b32_e32 v60, v62
	v_permlane16_swap_b32_e32 v61, v63
	v_permlane16_swap_b32_e32 v52, v54
	v_permlane16_swap_b32_e32 v53, v55
	global_store_dwordx4 v[246:247], v[60:63], off
	global_store_dwordx4 v[246:247], v[52:55], off offset:64
	v_add_co_u32_e32 v246, vcc, 0x2c000, v246
	s_nop 1
	v_addc_co_u32_e32 v247, vcc, 0, v247, vcc
	v_cvt_pk_bf16_f32 v44, v44, v45
	v_cvt_pk_bf16_f32 v45, v46, v47
	v_cvt_pk_bf16_f32 v46, v40, v41
	v_cvt_pk_bf16_f32 v47, v42, v43
	v_cvt_pk_bf16_f32 v36, v36, v37
	v_cvt_pk_bf16_f32 v37, v38, v39
	v_cvt_pk_bf16_f32 v38, v32, v33
	v_cvt_pk_bf16_f32 v39, v34, v35
	s_nop 1
	v_permlane16_swap_b32_e32 v44, v46
	v_permlane16_swap_b32_e32 v45, v47
	v_permlane16_swap_b32_e32 v36, v38
	v_permlane16_swap_b32_e32 v37, v39
	global_store_dwordx4 v[246:247], v[44:47], off
	global_store_dwordx4 v[246:247], v[36:39], off offset:64
	v_add_co_u32_e32 v246, vcc, 0x2c000, v246
	s_nop 1
	v_addc_co_u32_e32 v247, vcc, 0, v247, vcc
	v_cvt_pk_bf16_f32 v28, v28, v29
	v_cvt_pk_bf16_f32 v29, v30, v31
	v_cvt_pk_bf16_f32 v30, v24, v25
	v_cvt_pk_bf16_f32 v31, v26, v27
	v_cvt_pk_bf16_f32 v20, v20, v21
	v_cvt_pk_bf16_f32 v21, v22, v23
	v_cvt_pk_bf16_f32 v22, v16, v17
	v_cvt_pk_bf16_f32 v23, v18, v19
	s_nop 1
	v_permlane16_swap_b32_e32 v28, v30
	v_permlane16_swap_b32_e32 v29, v31
	v_permlane16_swap_b32_e32 v20, v22
	v_permlane16_swap_b32_e32 v21, v23
	global_store_dwordx4 v[246:247], v[28:31], off
	global_store_dwordx4 v[246:247], v[20:23], off offset:64
	v_add_co_u32_e32 v246, vcc, 0x2c000, v246
	s_nop 1
	v_addc_co_u32_e32 v247, vcc, 0, v247, vcc
	v_cvt_pk_bf16_f32 v12, v12, v13
	v_cvt_pk_bf16_f32 v13, v14, v15
	v_cvt_pk_bf16_f32 v14, v8, v9
	v_cvt_pk_bf16_f32 v15, v10, v11
	v_cvt_pk_bf16_f32 v4, v4, v5
	v_cvt_pk_bf16_f32 v5, v6, v7
	v_cvt_pk_bf16_f32 v6, v0, v1
	v_cvt_pk_bf16_f32 v7, v2, v3
	s_nop 1
	v_permlane16_swap_b32_e32 v12, v14
	v_permlane16_swap_b32_e32 v13, v15
	v_permlane16_swap_b32_e32 v4, v6
	v_permlane16_swap_b32_e32 v5, v7
	global_store_dwordx4 v[246:247], v[12:15], off
	global_store_dwordx4 v[246:247], v[4:7], off offset:64
	s_andn2_b64 vcc, exec, s[26:27]
	s_cbranch_vccz .LBB0_1666
